# retention prefetch: XNACK-replay s_nop pads between back-to-back global loads removed
# speedup vs baseline: 1.0025x; 1.0025x over previous
; #define LAS __attribute__((address_space(3)))
; __device__ __forceinline__ bf16_t f2bf(float f) { return (bf16_t)(cvtpk(f, 0.f) & 0xffffu); }
; __device__ __forceinline__ void ret_unit(LAS unsigned char* lds, bf16_t* U, bf16_t* OF, int b, int h, int sl, const int tid, const bool dry) {
;     ...
;       __syncthreads();
; #pragma unroll
;       for (int i = 0; i < 4; ++i) { const int idx = tid + 512 * i, row = idx >> 4, ch = idx & 15;
;         *(LAS u32x4*)(Qs + row * RT_STR + ch * 8) = rq[i]; *(LAS u32x4*)(Ks + row * RT_STR + ch * 8) = scale8(rk[i], kf4[i]); }
; #pragma unroll
;       for (int i = 0; i < 2; ++i) { const int idx = tid + 512 * i, row = idx >> 3, ch = idx & 7; *(LAS u32x4*)(Vs + row * RT_VSTR + ch * 8) = rv[i]; }
; #pragma unroll
;       for (int eb = 0; eb < 4; ++eb)
; #pragma unroll
;         for (int r = 0; r < 4; ++r) St[(16 * eb + 4 * quad + r) * RT_STR + 16 * wid + c16] = f2bf(st[eb][r]);
;       __syncthreads();
;       if (step + 1 < 66) { const int s1 = step + 1; const int c1 = dir ? ((s1 < 2) ? (1 - s1) : (67 - s1)) : s1; const size_t r1 = rowb + (size_t)c1 * 128;
; #pragma unroll
;         for (int i = 0; i < 4; ++i) { const int idx = tid + 512 * i, row = idx >> 4, ch = idx & 15; const bf16_t* src = U + (r1 + row) * 4096 + h * 128 + ch * 8; rq[i] = *(const u32x4*)src; rk[i] = *(const u32x4*)(src + 1024); }
; #pragma unroll
;         for (int i = 0; i < 2; ++i) { const int idx = tid + 512 * i, row = idx >> 3, ch = idx & 7; rv[i] = *(const u32x4*)(U + (r1 + row) * 4096 + 2048 + h * 256 + sl * 64 + ch * 8); } }
.LBB0_252:
	s_waitcnt vmcnt(8)
	v_lshlrev_b32_e32 v42, 16, v6
	v_and_b32_e32 v43, 0xffff0000, v6
	v_lshlrev_b32_e32 v44, 16, v7
	v_and_b32_e32 v45, 0xffff0000, v7
	v_pk_mul_f32 v[42:43], v[156:157], v[42:43]
	v_pk_mul_f32 v[44:45], v[156:157], v[44:45]
	v_cvt_pk_bf16_f32 v42, v42, v43
	v_cvt_pk_bf16_f32 v43, v44, v45
	v_lshlrev_b32_e32 v44, 16, v8
	v_and_b32_e32 v45, 0xffff0000, v8
	v_lshlrev_b32_e32 v46, 16, v9
	v_and_b32_e32 v47, 0xffff0000, v9
	v_pk_mul_f32 v[44:45], v[156:157], v[44:45]
	v_pk_mul_f32 v[46:47], v[156:157], v[46:47]
	v_cvt_pk_bf16_f32 v44, v44, v45
	v_cvt_pk_bf16_f32 v45, v46, v47
	s_barrier
	ds_write_b128 v126, v[2:5]
	ds_write_b128 v126, v[42:45] offset:34816
	s_waitcnt vmcnt(7)
	ds_write_b128 v128, v[10:13]
	s_waitcnt vmcnt(6)
	v_lshlrev_b32_e32 v42, 16, v14
	v_and_b32_e32 v43, 0xffff0000, v14
	v_lshlrev_b32_e32 v44, 16, v15
	v_and_b32_e32 v45, 0xffff0000, v15
	v_pk_mul_f32 v[42:43], v[158:159], v[42:43]
	v_pk_mul_f32 v[44:45], v[158:159], v[44:45]
	v_cvt_pk_bf16_f32 v42, v42, v43
	v_cvt_pk_bf16_f32 v43, v44, v45
	v_lshlrev_b32_e32 v44, 16, v16
	v_and_b32_e32 v45, 0xffff0000, v16
	v_lshlrev_b32_e32 v46, 16, v17
	v_and_b32_e32 v47, 0xffff0000, v17
	v_pk_mul_f32 v[44:45], v[158:159], v[44:45]
	v_pk_mul_f32 v[46:47], v[158:159], v[46:47]
	v_cvt_pk_bf16_f32 v44, v44, v45
	v_cvt_pk_bf16_f32 v45, v46, v47
	ds_write_b128 v128, v[42:45] offset:34816
	s_waitcnt vmcnt(5)
	ds_write_b128 v130, v[18:21]
	s_waitcnt vmcnt(4)
	v_lshlrev_b32_e32 v42, 16, v22
	v_and_b32_e32 v43, 0xffff0000, v22
	v_lshlrev_b32_e32 v44, 16, v23
	v_and_b32_e32 v45, 0xffff0000, v23
	v_pk_mul_f32 v[42:43], v[160:161], v[42:43]
	v_pk_mul_f32 v[44:45], v[160:161], v[44:45]
	v_cvt_pk_bf16_f32 v42, v42, v43
	v_cvt_pk_bf16_f32 v43, v44, v45
	v_lshlrev_b32_e32 v44, 16, v24
	v_and_b32_e32 v45, 0xffff0000, v24
	v_lshlrev_b32_e32 v46, 16, v25
	v_and_b32_e32 v47, 0xffff0000, v25
	v_pk_mul_f32 v[44:45], v[160:161], v[44:45]
	v_pk_mul_f32 v[46:47], v[160:161], v[46:47]
	v_cvt_pk_bf16_f32 v44, v44, v45
	v_cvt_pk_bf16_f32 v45, v46, v47
	ds_write_b128 v130, v[42:45] offset:34816
	s_waitcnt vmcnt(3)
	ds_write_b128 v132, v[26:29]
	s_waitcnt vmcnt(2)
	v_lshlrev_b32_e32 v42, 16, v30
	v_and_b32_e32 v43, 0xffff0000, v30
	v_lshlrev_b32_e32 v44, 16, v31
	v_and_b32_e32 v45, 0xffff0000, v31
	v_pk_mul_f32 v[42:43], v[162:163], v[42:43]
	v_pk_mul_f32 v[44:45], v[162:163], v[44:45]
	v_cvt_pk_bf16_f32 v42, v42, v43
	v_cvt_pk_bf16_f32 v43, v44, v45
	v_lshlrev_b32_e32 v44, 16, v32
	v_and_b32_e32 v45, 0xffff0000, v32
	v_lshlrev_b32_e32 v46, 16, v33
	v_and_b32_e32 v47, 0xffff0000, v33
	v_pk_mul_f32 v[44:45], v[162:163], v[44:45]
	v_pk_mul_f32 v[46:47], v[162:163], v[46:47]
	v_cvt_pk_bf16_f32 v44, v44, v45
	v_cvt_pk_bf16_f32 v45, v46, v47
	ds_write_b128 v132, v[42:45] offset:34816
	s_waitcnt vmcnt(1)
	ds_write_b128 v127, v[34:37]
	s_waitcnt vmcnt(0)
	ds_write_b128 v129, v[38:41]
	v_cvt_pk_bf16_f32 v42, v94, s0
	ds_write_b16 v131, v42
	v_cvt_pk_bf16_f32 v42, v95, s0
	ds_write_b16 v131, v42 offset:272
	v_cvt_pk_bf16_f32 v42, v96, s0
	ds_write_b16 v133, v42
	v_cvt_pk_bf16_f32 v42, v97, s0
	ds_write_b16 v133, v42 offset:272
	v_cvt_pk_bf16_f32 v42, v98, s0
	ds_write_b16 v133, v42 offset:3808
	v_cvt_pk_bf16_f32 v42, v99, s0
	ds_write_b16 v133, v42 offset:4080
	v_cvt_pk_bf16_f32 v42, v100, s0
	ds_write_b16 v133, v42 offset:4352
	v_cvt_pk_bf16_f32 v42, v101, s0
	ds_write_b16 v133, v42 offset:4624
	v_cvt_pk_bf16_f32 v42, v102, s0
	ds_write_b16 v133, v42 offset:8160
	v_cvt_pk_bf16_f32 v42, v103, s0
	ds_write_b16 v133, v42 offset:8432
	v_cvt_pk_bf16_f32 v42, v104, s0
	ds_write_b16 v133, v42 offset:8704
	v_cvt_pk_bf16_f32 v42, v105, s0
	ds_write_b16 v133, v42 offset:8976
	v_cvt_pk_bf16_f32 v42, v174, s0
	ds_write_b16 v133, v42 offset:12512
	v_cvt_pk_bf16_f32 v42, v175, s0
	ds_write_b16 v133, v42 offset:12784
	v_cvt_pk_bf16_f32 v42, v176, s0
	s_add_i32 s91, s88, 1
	ds_write_b16 v133, v42 offset:13056
	v_cvt_pk_bf16_f32 v42, v177, s0
	s_cmp_eq_u32 s83, 1
	ds_write_b16 v133, v42 offset:13328
	s_waitcnt lgkmcnt(0)
	s_barrier
	s_cbranch_scc1 .LBB0_254
	s_cmp_lg_u32 s88, 0
	s_cselect_b32 s86, s83, 0
	s_and_b64 vcc, s[8:9], exec
	s_cselect_b32 s86, s91, s86
	s_lshl_b64 vcc, s[86:87], 7
	s_add_u32 s92, vcc_lo, s82
	s_addc_u32 s93, vcc_hi, 0
	v_lshl_add_u64 v[34:35], s[92:93], 0, v[122:123]
	v_lshlrev_b64 v[34:35], 13, v[34:35]
	v_lshl_add_u64 v[34:35], s[84:85], 0, v[34:35]
	v_lshl_add_u64 v[36:37], s[92:93], 0, v[124:125]
	v_lshl_add_u64 v[34:35], v[34:35], 0, s[6:7]
	s_mov_b32 s95, s87
	v_lshlrev_b64 v[36:37], 13, v[36:37]
	v_lshl_add_u64 v[34:35], v[34:35], 0, s[94:95]
	v_lshl_add_u64 v[36:37], s[84:85], 0, v[36:37]
	v_lshl_add_u64 v[34:35], v[34:35], 0, v[0:1]
	s_movk_i32 s86, 0x1000
	v_lshl_add_u64 v[36:37], v[36:37], 0, s[6:7]
	v_add_co_u32_e32 v34, vcc, s86, v34
	v_lshl_add_u64 v[36:37], v[36:37], 0, s[94:95]
	v_lshl_add_u64 v[2:3], s[92:93], 0, v[114:115]
	v_lshl_add_u64 v[10:11], s[92:93], 0, v[116:117]
	v_lshl_add_u64 v[18:19], s[92:93], 0, v[118:119]
	v_lshl_add_u64 v[26:27], s[92:93], 0, v[120:121]
	v_addc_co_u32_e32 v35, vcc, 0, v35, vcc
	v_lshl_add_u64 v[36:37], v[36:37], 0, v[0:1]
	v_lshlrev_b64 v[2:3], 13, v[2:3]
	v_lshlrev_b64 v[10:11], 13, v[10:11]
	v_lshlrev_b64 v[18:19], 13, v[18:19]
	v_lshlrev_b64 v[26:27], 13, v[26:27]
	v_add_co_u32_e32 v38, vcc, 0x1000, v36
	v_lshl_add_u64 v[6:7], v[134:135], 0, v[2:3]
	v_lshl_add_u64 v[14:15], v[134:135], 0, v[10:11]
	v_lshl_add_u64 v[22:23], v[134:135], 0, v[18:19]
	v_lshl_add_u64 v[30:31], v[134:135], 0, v[26:27]
	v_addc_co_u32_e32 v39, vcc, 0, v37, vcc
	global_load_dwordx4 v[2:5], v[6:7], off
	global_load_dwordx4 v[6:9], v[6:7], off offset:2048
	global_load_dwordx4 v[10:13], v[14:15], off
	global_load_dwordx4 v[14:17], v[14:15], off offset:2048
	global_load_dwordx4 v[18:21], v[22:23], off
	global_load_dwordx4 v[22:25], v[22:23], off offset:2048
	global_load_dwordx4 v[26:29], v[30:31], off
	global_load_dwordx4 v[30:33], v[30:31], off offset:2048
	global_load_dwordx4 v[34:37], v[34:35], off
	global_load_dwordx4 v[38:41], v[38:39], off
